# also the gate/in-projection main loop's accumulate chains issued back-to-back (dependency-checked reorder)
# speedup vs baseline: 1.0082x; 1.0020x over previous
.LBB0_638:
	s_ashr_i32 s87, s86, 31
	s_lshl_b64 s[40:41], s[86:87], 20
	s_add_u32 s88, s14, s40
	s_addc_u32 s89, s15, s41
	s_and_b64 s[40:41], s[4:5], exec
	s_cselect_b32 s7, s89, s11
	s_cselect_b32 s9, s88, s10
	s_ashr_i32 s85, s84, 31
	s_lshl_b64 s[40:41], s[84:85], 20
	s_add_u32 s90, s24, s40
	s_addc_u32 s91, s26, s41
	s_and_b64 s[40:41], s[4:5], exec
	s_cselect_b32 s40, s91, s93
	s_cselect_b32 s41, s90, s92
	s_add_u32 s10, s10, 0x80080
	s_addc_u32 s11, s11, 0
	s_add_u32 s54, s92, 0x100
	s_addc_u32 s55, s93, 0
	s_mov_b32 s85, -2
	s_add_u32 s67, s10, 0xfff80080
	s_addc_u32 s87, s11, -1
	s_add_i32 s96, 0, 0x10000
	s_cmp_eq_u32 s85, 28
	s_cselect_b32 s95, s7, s87
	s_cselect_b32 s94, s9, s67
	s_cselect_b32 s93, s40, s55
	s_cselect_b32 s92, s41, s54
	s_add_i32 s67, 0, 0x14000
	v_add_u32_e32 v52, s96, v194
	v_add_u32_e32 v124, s67, v194
	ds_read_b128 v[40:43], v52
	ds_read_b128 v[44:47], v52 offset:1024
	ds_read_b128 v[48:51], v52 offset:2048
	ds_read_b128 v[52:55], v52 offset:3072
	ds_read_b128 v[64:67], v124
	ds_read_b128 v[100:103], v124 offset:1024
	ds_read_b128 v[120:123], v124 offset:2048
	ds_read_b128 v[124:127], v124 offset:3072
	v_lshl_add_u64 v[208:209], s[10:11], 0, v[186:187]
	s_add_i32 m0, s57, 0xc000
	ds_read_b128 v[136:139], v195
	ds_read_b128 v[140:143], v195 offset:1024
	ds_read_b128 v[144:147], v195 offset:2048
	ds_read_b128 v[172:175], v195 offset:3072
	ds_read_b128 v[190:193], v195 offset:4096
	ds_read_b128 v[196:199], v195 offset:5120
	ds_read_b128 v[200:203], v195 offset:6144
	ds_read_b128 v[204:207], v195 offset:7168
	global_load_lds_dwordx4 v[208:209], off
	v_lshl_add_u64 v[208:209], s[10:11], 0, v[188:189]
	s_add_i32 m0, s57, 0xe000
	s_nop 0
	global_load_lds_dwordx4 v[208:209], off
	s_waitcnt vmcnt(8)
	s_waitcnt lgkmcnt(0)
	s_barrier
	s_waitcnt lgkmcnt(0)
	v_mfma_f32_16x16x32_bf16 v[168:171], v[40:43], v[136:139], 0
	v_mfma_f32_16x16x32_bf16 v[168:171], v[44:47], v[140:143], v[168:171]
	v_mfma_f32_16x16x32_bf16 v[164:167], v[48:51], v[136:139], 0
	v_mfma_f32_16x16x32_bf16 v[164:167], v[52:55], v[140:143], v[164:167]
	v_mfma_f32_16x16x32_bf16 v[152:155], v[40:43], v[144:147], 0
	v_mfma_f32_16x16x32_bf16 v[152:155], v[44:47], v[172:175], v[152:155]
	v_mfma_f32_16x16x32_bf16 v[148:151], v[48:51], v[144:147], 0
	v_mfma_f32_16x16x32_bf16 v[148:151], v[52:55], v[172:175], v[148:151]
	v_mfma_f32_16x16x32_bf16 v[116:119], v[40:43], v[190:193], 0
	v_mfma_f32_16x16x32_bf16 v[116:119], v[44:47], v[196:199], v[116:119]
	v_mfma_f32_16x16x32_bf16 v[112:115], v[48:51], v[190:193], 0
	v_mfma_f32_16x16x32_bf16 v[112:115], v[52:55], v[196:199], v[112:115]
	v_mfma_f32_16x16x32_bf16 v[96:99], v[40:43], v[200:203], 0
	v_mfma_f32_16x16x32_bf16 v[96:99], v[44:47], v[204:207], v[96:99]
	v_mfma_f32_16x16x32_bf16 v[92:95], v[48:51], v[200:203], 0
	v_mfma_f32_16x16x32_bf16 v[92:95], v[52:55], v[204:207], v[92:95]
	v_mfma_f32_16x16x32_bf16 v[160:163], v[64:67], v[136:139], 0
	v_mfma_f32_16x16x32_bf16 v[160:163], v[100:103], v[140:143], v[160:163]
	v_mfma_f32_16x16x32_bf16 v[132:135], v[64:67], v[144:147], 0
	v_mfma_f32_16x16x32_bf16 v[132:135], v[100:103], v[172:175], v[132:135]
	v_mfma_f32_16x16x32_bf16 v[128:131], v[120:123], v[144:147], 0
	v_mfma_f32_16x16x32_bf16 v[128:131], v[124:127], v[172:175], v[128:131]
	v_mfma_f32_16x16x32_bf16 v[108:111], v[64:67], v[190:193], 0
	v_mfma_f32_16x16x32_bf16 v[108:111], v[100:103], v[196:199], v[108:111]
	v_mfma_f32_16x16x32_bf16 v[104:107], v[120:123], v[190:193], 0
	v_mfma_f32_16x16x32_bf16 v[104:107], v[124:127], v[196:199], v[104:107]
	v_mfma_f32_16x16x32_bf16 v[88:91], v[64:67], v[200:203], 0
	v_mfma_f32_16x16x32_bf16 v[88:91], v[100:103], v[204:207], v[88:91]
	v_mfma_f32_16x16x32_bf16 v[84:87], v[120:123], v[200:203], 0
	v_mfma_f32_16x16x32_bf16 v[84:87], v[124:127], v[204:207], v[84:87]
	v_mfma_f32_16x16x32_bf16 v[136:139], v[120:123], v[136:139], 0
	v_mfma_f32_16x16x32_bf16 v[136:139], v[124:127], v[140:143], v[136:139]
	s_barrier
	s_add_i32 s87, s96, s56
	v_lshl_add_u64 v[212:213], s[92:93], 0, v[178:179]
	s_mov_b32 m0, s87
	ds_read_b128 v[140:143], v195 offset:16384
	ds_read_b128 v[144:147], v195 offset:17408
	ds_read_b128 v[156:159], v195 offset:18432
	ds_read_b128 v[172:175], v195 offset:19456
	ds_read_b128 v[190:193], v195 offset:20480
	ds_read_b128 v[196:199], v195 offset:21504
	ds_read_b128 v[200:203], v195 offset:22528
	ds_read_b128 v[204:207], v195 offset:23552
	global_load_lds_dwordx4 v[212:213], off
	s_add_i32 m0, s87, 0x2000
	s_add_u32 vcc_lo, s92, 0x80000
	v_lshl_add_u64 v[214:215], s[92:93], 0, v[182:183]
	s_addc_u32 vcc_hi, s93, 0
	s_add_i32 s67, s67, s56
	global_load_lds_dwordx4 v[214:215], off
	v_lshl_add_u64 v[208:209], vcc, 0, v[178:179]
	s_mov_b32 m0, s67
	v_lshl_add_u64 v[224:225], s[94:95], 0, v[176:177]
	global_load_lds_dwordx4 v[208:209], off
	v_lshl_add_u64 v[208:209], vcc, 0, v[182:183]
	s_add_i32 m0, s67, 0x2000
	v_lshl_add_u64 v[226:227], s[94:95], 0, v[180:181]
	global_load_lds_dwordx4 v[208:209], off
	s_mov_b32 m0, s57
	s_nop 0
	global_load_lds_dwordx4 v[224:225], off
	s_mov_b32 m0, s61
	s_nop 0
	global_load_lds_dwordx4 v[226:227], off
	s_waitcnt vmcnt(8)
	s_waitcnt lgkmcnt(0)
	s_barrier
	s_waitcnt lgkmcnt(0)
	v_mfma_f32_16x16x32_bf16 v[80:83], v[40:43], v[140:143], 0
	v_mfma_f32_16x16x32_bf16 v[80:83], v[44:47], v[144:147], v[80:83]
	v_mfma_f32_16x16x32_bf16 v[76:79], v[48:51], v[140:143], 0
	v_mfma_f32_16x16x32_bf16 v[76:79], v[52:55], v[144:147], v[76:79]
	v_mfma_f32_16x16x32_bf16 v[60:63], v[40:43], v[156:159], 0
	v_mfma_f32_16x16x32_bf16 v[60:63], v[44:47], v[172:175], v[60:63]
	v_mfma_f32_16x16x32_bf16 v[56:59], v[48:51], v[156:159], 0
	v_mfma_f32_16x16x32_bf16 v[56:59], v[52:55], v[172:175], v[56:59]
	v_mfma_f32_16x16x32_bf16 v[28:31], v[40:43], v[190:193], 0
	v_mfma_f32_16x16x32_bf16 v[28:31], v[44:47], v[196:199], v[28:31]
	v_mfma_f32_16x16x32_bf16 v[24:27], v[48:51], v[190:193], 0
	v_mfma_f32_16x16x32_bf16 v[24:27], v[52:55], v[196:199], v[24:27]
	v_mfma_f32_16x16x32_bf16 v[12:15], v[40:43], v[200:203], 0
	v_mfma_f32_16x16x32_bf16 v[12:15], v[44:47], v[204:207], v[12:15]
	v_mfma_f32_16x16x32_bf16 v[8:11], v[48:51], v[200:203], 0
	v_mfma_f32_16x16x32_bf16 v[8:11], v[52:55], v[204:207], v[8:11]
	v_mfma_f32_16x16x32_bf16 v[36:39], v[64:67], v[156:159], 0
	v_mfma_f32_16x16x32_bf16 v[36:39], v[100:103], v[172:175], v[36:39]
	v_mfma_f32_16x16x32_bf16 v[32:35], v[120:123], v[156:159], 0
	v_mfma_f32_16x16x32_bf16 v[32:35], v[124:127], v[172:175], v[32:35]
	v_mfma_f32_16x16x32_bf16 v[20:23], v[64:67], v[190:193], 0
	v_mfma_f32_16x16x32_bf16 v[20:23], v[100:103], v[196:199], v[20:23]
	v_mfma_f32_16x16x32_bf16 v[16:19], v[120:123], v[190:193], 0
	v_mfma_f32_16x16x32_bf16 v[16:19], v[124:127], v[196:199], v[16:19]
	v_mfma_f32_16x16x32_bf16 v[4:7], v[64:67], v[200:203], 0
	v_mfma_f32_16x16x32_bf16 v[4:7], v[100:103], v[204:207], v[4:7]
	v_mfma_f32_16x16x32_bf16 v[0:3], v[120:123], v[200:203], 0
	v_mfma_f32_16x16x32_bf16 v[0:3], v[124:127], v[204:207], v[0:3]
	v_mfma_f32_16x16x32_bf16 v[40:43], v[64:67], v[140:143], 0
	v_mfma_f32_16x16x32_bf16 v[40:43], v[100:103], v[144:147], v[40:43]
	v_mfma_f32_16x16x32_bf16 v[44:47], v[120:123], v[140:143], 0
	v_mfma_f32_16x16x32_bf16 v[44:47], v[124:127], v[144:147], v[44:47]
	s_barrier
	s_add_i32 s67, 0, 0x18000
	s_add_i32 s87, 0, 0x1c000
	v_add_u32_e32 v68, s67, v194
	v_add_u32_e32 v72, s87, v194
	ds_read_b128 v[48:51], v68
	ds_read_b128 v[52:55], v68 offset:1024
	ds_read_b128 v[64:67], v68 offset:2048
	ds_read_b128 v[68:71], v68 offset:3072
	ds_read_b128 v[100:103], v72
	ds_read_b128 v[120:123], v72 offset:1024
	ds_read_b128 v[124:127], v72 offset:2048
	ds_read_b128 v[140:143], v72 offset:3072
	s_add_u32 s94, s94, 0x80000
	s_addc_u32 s95, s95, 0
	s_mov_b32 m0, s68
	v_lshl_add_u64 v[156:157], s[94:95], 0, v[176:177]
	ds_read_b128 v[72:75], v195 offset:32768
	ds_read_b128 v[144:147], v195 offset:33792
	ds_read_b128 v[172:175], v195 offset:34816
	ds_read_b128 v[190:193], v195 offset:35840
	ds_read_b128 v[196:199], v195 offset:36864
	ds_read_b128 v[200:203], v195 offset:37888
	ds_read_b128 v[204:207], v195 offset:38912
	ds_read_b128 v[208:211], v195 offset:39936
	global_load_lds_dwordx4 v[156:157], off
	v_lshl_add_u64 v[156:157], s[94:95], 0, v[180:181]
	s_mov_b32 m0, s69
	s_nop 0
	global_load_lds_dwordx4 v[156:157], off
	s_waitcnt vmcnt(8)
	s_waitcnt lgkmcnt(0)
	s_barrier
	s_waitcnt lgkmcnt(0)
	v_mfma_f32_16x16x32_bf16 v[156:159], v[48:51], v[72:75], v[168:171]
	v_mfma_f32_16x16x32_bf16 v[168:171], v[52:55], v[144:147], v[156:159]
	v_mfma_f32_16x16x32_bf16 v[156:159], v[64:67], v[72:75], v[164:167]
	v_mfma_f32_16x16x32_bf16 v[164:167], v[68:71], v[144:147], v[156:159]
	v_mfma_f32_16x16x32_bf16 v[152:155], v[48:51], v[172:175], v[152:155]
	v_mfma_f32_16x16x32_bf16 v[152:155], v[52:55], v[190:193], v[152:155]
	v_mfma_f32_16x16x32_bf16 v[148:151], v[64:67], v[172:175], v[148:151]
	v_mfma_f32_16x16x32_bf16 v[148:151], v[68:71], v[190:193], v[148:151]
	v_mfma_f32_16x16x32_bf16 v[116:119], v[48:51], v[196:199], v[116:119]
	v_mfma_f32_16x16x32_bf16 v[116:119], v[52:55], v[200:203], v[116:119]
	v_mfma_f32_16x16x32_bf16 v[112:115], v[64:67], v[196:199], v[112:115]
	v_mfma_f32_16x16x32_bf16 v[112:115], v[68:71], v[200:203], v[112:115]
	v_mfma_f32_16x16x32_bf16 v[96:99], v[48:51], v[204:207], v[96:99]
	v_mfma_f32_16x16x32_bf16 v[96:99], v[52:55], v[208:211], v[96:99]
	v_mfma_f32_16x16x32_bf16 v[92:95], v[64:67], v[204:207], v[92:95]
	v_mfma_f32_16x16x32_bf16 v[92:95], v[68:71], v[208:211], v[92:95]
	v_mfma_f32_16x16x32_bf16 v[156:159], v[100:103], v[72:75], v[160:163]
	v_mfma_f32_16x16x32_bf16 v[160:163], v[120:123], v[144:147], v[156:159]
	v_mfma_f32_16x16x32_bf16 v[72:75], v[124:127], v[72:75], v[136:139]
	v_mfma_f32_16x16x32_bf16 v[156:159], v[140:143], v[144:147], v[72:75]
	v_mfma_f32_16x16x32_bf16 v[72:75], v[100:103], v[172:175], v[132:135]
	v_mfma_f32_16x16x32_bf16 v[132:135], v[120:123], v[190:193], v[72:75]
	v_mfma_f32_16x16x32_bf16 v[72:75], v[124:127], v[172:175], v[128:131]
	v_mfma_f32_16x16x32_bf16 v[128:131], v[140:143], v[190:193], v[72:75]
	v_mfma_f32_16x16x32_bf16 v[72:75], v[100:103], v[196:199], v[108:111]
	v_mfma_f32_16x16x32_bf16 v[108:111], v[120:123], v[200:203], v[72:75]
	v_mfma_f32_16x16x32_bf16 v[72:75], v[124:127], v[196:199], v[104:107]
	v_mfma_f32_16x16x32_bf16 v[104:107], v[140:143], v[200:203], v[72:75]
	v_mfma_f32_16x16x32_bf16 v[72:75], v[100:103], v[204:207], v[88:91]
	v_mfma_f32_16x16x32_bf16 v[88:91], v[120:123], v[208:211], v[72:75]
	v_mfma_f32_16x16x32_bf16 v[72:75], v[124:127], v[204:207], v[84:87]
	v_mfma_f32_16x16x32_bf16 v[84:87], v[140:143], v[208:211], v[72:75]
	s_barrier
	s_add_i32 s67, s67, s56
	s_nop 3
	v_lshl_add_u64 v[72:73], v[212:213], 0, s[30:31]
	s_mov_b32 m0, s67
	ds_read_b128 v[136:139], v195 offset:49152
	ds_read_b128 v[144:147], v195 offset:50176
	ds_read_b128 v[172:175], v195 offset:51200
	ds_read_b128 v[190:193], v195 offset:52224
	ds_read_b128 v[196:199], v195 offset:53248
	ds_read_b128 v[200:203], v195 offset:54272
	ds_read_b128 v[204:207], v195 offset:55296
	ds_read_b128 v[208:211], v195 offset:56320
	global_load_lds_dwordx4 v[72:73], off
	s_add_i32 m0, s67, 0x2000
	s_add_u32 s92, s92, 0x80080
	v_lshl_add_u64 v[72:73], v[214:215], 0, s[30:31]
	s_addc_u32 s93, s93, 0
	s_add_i32 s67, s87, s56
	global_load_lds_dwordx4 v[72:73], off
	v_lshl_add_u64 v[72:73], s[92:93], 0, v[178:179]
	s_mov_b32 m0, s67
	s_nop 0
	global_load_lds_dwordx4 v[72:73], off
	v_lshl_add_u64 v[72:73], s[92:93], 0, v[182:183]
	s_add_i32 m0, s67, 0x2000
	s_nop 0
	global_load_lds_dwordx4 v[72:73], off
	v_lshl_add_u64 v[72:73], v[224:225], 0, s[30:31]
	s_mov_b32 m0, s2
	s_nop 0
	global_load_lds_dwordx4 v[72:73], off
	v_lshl_add_u64 v[72:73], v[226:227], 0, s[30:31]
	s_mov_b32 m0, s28
	s_nop 0
	global_load_lds_dwordx4 v[72:73], off
	s_waitcnt vmcnt(8)
	s_waitcnt lgkmcnt(0)
	s_barrier
	s_waitcnt lgkmcnt(0)
	v_mfma_f32_16x16x32_bf16 v[72:75], v[48:51], v[136:139], v[80:83]
	v_mfma_f32_16x16x32_bf16 v[80:83], v[52:55], v[144:147], v[72:75]
	v_mfma_f32_16x16x32_bf16 v[72:75], v[64:67], v[136:139], v[76:79]
	v_mfma_f32_16x16x32_bf16 v[76:79], v[68:71], v[144:147], v[72:75]
	v_mfma_f32_16x16x32_bf16 v[60:63], v[48:51], v[172:175], v[60:63]
	v_mfma_f32_16x16x32_bf16 v[60:63], v[52:55], v[190:193], v[60:63]
	v_mfma_f32_16x16x32_bf16 v[56:59], v[64:67], v[172:175], v[56:59]
	v_mfma_f32_16x16x32_bf16 v[56:59], v[68:71], v[190:193], v[56:59]
	v_mfma_f32_16x16x32_bf16 v[28:31], v[48:51], v[196:199], v[28:31]
	v_mfma_f32_16x16x32_bf16 v[28:31], v[52:55], v[200:203], v[28:31]
	v_mfma_f32_16x16x32_bf16 v[24:27], v[64:67], v[196:199], v[24:27]
	v_mfma_f32_16x16x32_bf16 v[24:27], v[68:71], v[200:203], v[24:27]
	v_mfma_f32_16x16x32_bf16 v[12:15], v[48:51], v[204:207], v[12:15]
	v_mfma_f32_16x16x32_bf16 v[12:15], v[52:55], v[208:211], v[12:15]
	v_mfma_f32_16x16x32_bf16 v[8:11], v[64:67], v[204:207], v[8:11]
	v_mfma_f32_16x16x32_bf16 v[8:11], v[68:71], v[208:211], v[8:11]
	v_mfma_f32_16x16x32_bf16 v[40:43], v[100:103], v[136:139], v[40:43]
	v_mfma_f32_16x16x32_bf16 v[72:75], v[120:123], v[144:147], v[40:43]
	v_mfma_f32_16x16x32_bf16 v[40:43], v[124:127], v[136:139], v[44:47]
	v_mfma_f32_16x16x32_bf16 v[68:71], v[140:143], v[144:147], v[40:43]
	v_mfma_f32_16x16x32_bf16 v[36:39], v[100:103], v[172:175], v[36:39]
	v_mfma_f32_16x16x32_bf16 v[36:39], v[120:123], v[190:193], v[36:39]
	v_mfma_f32_16x16x32_bf16 v[32:35], v[124:127], v[172:175], v[32:35]
	v_mfma_f32_16x16x32_bf16 v[32:35], v[140:143], v[190:193], v[32:35]
	v_mfma_f32_16x16x32_bf16 v[20:23], v[100:103], v[196:199], v[20:23]
	v_mfma_f32_16x16x32_bf16 v[20:23], v[120:123], v[200:203], v[20:23]
	v_mfma_f32_16x16x32_bf16 v[16:19], v[124:127], v[196:199], v[16:19]
	v_mfma_f32_16x16x32_bf16 v[16:19], v[140:143], v[200:203], v[16:19]
	v_mfma_f32_16x16x32_bf16 v[4:7], v[100:103], v[204:207], v[4:7]
	v_mfma_f32_16x16x32_bf16 v[4:7], v[120:123], v[208:211], v[4:7]
	v_mfma_f32_16x16x32_bf16 v[0:3], v[124:127], v[204:207], v[0:3]
	v_mfma_f32_16x16x32_bf16 v[0:3], v[140:143], v[208:211], v[0:3]
	s_barrier
	s_add_i32 s85, s85, 2
	s_add_u32 s10, s10, 0x100
	s_addc_u32 s11, s11, 0
	s_add_u32 s54, s54, 0x100
	s_addc_u32 s55, s55, 0
.LBB0_639:
	s_add_u32 s67, s10, 0xfff80080
	s_addc_u32 s87, s11, -1
	s_add_i32 s96, 0, 0x10000
	s_cmp_eq_u32 s85, 28
	s_cselect_b32 s95, s7, s87
	s_cselect_b32 s94, s9, s67
	s_cselect_b32 s93, s40, s55
	s_cselect_b32 s92, s41, s54
	s_add_i32 s67, 0, 0x14000
	v_add_u32_e32 v52, s96, v194
	v_add_u32_e32 v124, s67, v194
	ds_read_b128 v[40:43], v52
	ds_read_b128 v[44:47], v52 offset:1024
	ds_read_b128 v[48:51], v52 offset:2048
	ds_read_b128 v[52:55], v52 offset:3072
	ds_read_b128 v[64:67], v124
	ds_read_b128 v[100:103], v124 offset:1024
	ds_read_b128 v[120:123], v124 offset:2048
	ds_read_b128 v[124:127], v124 offset:3072
	v_lshl_add_u64 v[208:209], s[10:11], 0, v[186:187]
	s_add_i32 m0, s57, 0xc000
	ds_read_b128 v[136:139], v195
	ds_read_b128 v[140:143], v195 offset:1024
	ds_read_b128 v[144:147], v195 offset:2048
	ds_read_b128 v[172:175], v195 offset:3072
	ds_read_b128 v[190:193], v195 offset:4096
	ds_read_b128 v[196:199], v195 offset:5120
	ds_read_b128 v[200:203], v195 offset:6144
	ds_read_b128 v[204:207], v195 offset:7168
	global_load_lds_dwordx4 v[208:209], off
	v_lshl_add_u64 v[208:209], s[10:11], 0, v[188:189]
	s_add_i32 m0, s57, 0xe000
	s_nop 0
	global_load_lds_dwordx4 v[208:209], off
	s_waitcnt vmcnt(8)
	s_waitcnt lgkmcnt(0)
	s_barrier
	s_waitcnt lgkmcnt(0)
	v_mfma_f32_16x16x32_bf16 v[168:171], v[40:43], v[136:139], v[168:171]
	v_mfma_f32_16x16x32_bf16 v[168:171], v[44:47], v[140:143], v[168:171]
	v_mfma_f32_16x16x32_bf16 v[164:167], v[48:51], v[136:139], v[164:167]
	v_mfma_f32_16x16x32_bf16 v[164:167], v[52:55], v[140:143], v[164:167]
	v_mfma_f32_16x16x32_bf16 v[152:155], v[40:43], v[144:147], v[152:155]
	v_mfma_f32_16x16x32_bf16 v[152:155], v[44:47], v[172:175], v[152:155]
	v_mfma_f32_16x16x32_bf16 v[148:151], v[48:51], v[144:147], v[148:151]
	v_mfma_f32_16x16x32_bf16 v[148:151], v[52:55], v[172:175], v[148:151]
	v_mfma_f32_16x16x32_bf16 v[116:119], v[40:43], v[190:193], v[116:119]
	v_mfma_f32_16x16x32_bf16 v[116:119], v[44:47], v[196:199], v[116:119]
	v_mfma_f32_16x16x32_bf16 v[112:115], v[48:51], v[190:193], v[112:115]
	v_mfma_f32_16x16x32_bf16 v[112:115], v[52:55], v[196:199], v[112:115]
	v_mfma_f32_16x16x32_bf16 v[96:99], v[40:43], v[200:203], v[96:99]
	v_mfma_f32_16x16x32_bf16 v[96:99], v[44:47], v[204:207], v[96:99]
	v_mfma_f32_16x16x32_bf16 v[92:95], v[48:51], v[200:203], v[92:95]
	v_mfma_f32_16x16x32_bf16 v[92:95], v[52:55], v[204:207], v[92:95]
	v_mfma_f32_16x16x32_bf16 v[160:163], v[64:67], v[136:139], v[160:163]
	v_mfma_f32_16x16x32_bf16 v[160:163], v[100:103], v[140:143], v[160:163]
	v_mfma_f32_16x16x32_bf16 v[132:135], v[64:67], v[144:147], v[132:135]
	v_mfma_f32_16x16x32_bf16 v[132:135], v[100:103], v[172:175], v[132:135]
	v_mfma_f32_16x16x32_bf16 v[128:131], v[120:123], v[144:147], v[128:131]
	v_mfma_f32_16x16x32_bf16 v[128:131], v[124:127], v[172:175], v[128:131]
	v_mfma_f32_16x16x32_bf16 v[108:111], v[64:67], v[190:193], v[108:111]
	v_mfma_f32_16x16x32_bf16 v[108:111], v[100:103], v[196:199], v[108:111]
	v_mfma_f32_16x16x32_bf16 v[104:107], v[120:123], v[190:193], v[104:107]
	v_mfma_f32_16x16x32_bf16 v[104:107], v[124:127], v[196:199], v[104:107]
	v_mfma_f32_16x16x32_bf16 v[88:91], v[64:67], v[200:203], v[88:91]
	v_mfma_f32_16x16x32_bf16 v[88:91], v[100:103], v[204:207], v[88:91]
	v_mfma_f32_16x16x32_bf16 v[84:87], v[120:123], v[200:203], v[84:87]
	v_mfma_f32_16x16x32_bf16 v[84:87], v[124:127], v[204:207], v[84:87]
	v_mfma_f32_16x16x32_bf16 v[136:139], v[120:123], v[136:139], v[156:159]
	v_mfma_f32_16x16x32_bf16 v[136:139], v[124:127], v[140:143], v[136:139]
	s_barrier
	s_add_i32 s87, s96, s56
	v_lshl_add_u64 v[212:213], s[92:93], 0, v[178:179]
	s_mov_b32 m0, s87
	ds_read_b128 v[140:143], v195 offset:16384
	ds_read_b128 v[144:147], v195 offset:17408
	ds_read_b128 v[156:159], v195 offset:18432
	ds_read_b128 v[172:175], v195 offset:19456
	ds_read_b128 v[190:193], v195 offset:20480
	ds_read_b128 v[196:199], v195 offset:21504
	ds_read_b128 v[200:203], v195 offset:22528
	ds_read_b128 v[204:207], v195 offset:23552
	global_load_lds_dwordx4 v[212:213], off
	s_add_i32 m0, s87, 0x2000
	s_add_u32 vcc_lo, s92, 0x80000
	v_lshl_add_u64 v[214:215], s[92:93], 0, v[182:183]
	s_addc_u32 vcc_hi, s93, 0
	s_add_i32 s67, s67, s56
	global_load_lds_dwordx4 v[214:215], off
	v_lshl_add_u64 v[208:209], vcc, 0, v[178:179]
	s_mov_b32 m0, s67
	v_lshl_add_u64 v[224:225], s[94:95], 0, v[176:177]
	global_load_lds_dwordx4 v[208:209], off
	v_lshl_add_u64 v[208:209], vcc, 0, v[182:183]
	s_add_i32 m0, s67, 0x2000
	v_lshl_add_u64 v[226:227], s[94:95], 0, v[180:181]
	global_load_lds_dwordx4 v[208:209], off
	s_mov_b32 m0, s57
	s_nop 0
	global_load_lds_dwordx4 v[224:225], off
	s_mov_b32 m0, s61
	s_nop 0
	global_load_lds_dwordx4 v[226:227], off
	s_waitcnt vmcnt(8)
	s_waitcnt lgkmcnt(0)
	s_barrier
	s_waitcnt lgkmcnt(0)
	v_mfma_f32_16x16x32_bf16 v[80:83], v[40:43], v[140:143], v[80:83]
	v_mfma_f32_16x16x32_bf16 v[80:83], v[44:47], v[144:147], v[80:83]
	v_mfma_f32_16x16x32_bf16 v[76:79], v[48:51], v[140:143], v[76:79]
	v_mfma_f32_16x16x32_bf16 v[76:79], v[52:55], v[144:147], v[76:79]
	v_mfma_f32_16x16x32_bf16 v[60:63], v[40:43], v[156:159], v[60:63]
	v_mfma_f32_16x16x32_bf16 v[60:63], v[44:47], v[172:175], v[60:63]
	v_mfma_f32_16x16x32_bf16 v[56:59], v[48:51], v[156:159], v[56:59]
	v_mfma_f32_16x16x32_bf16 v[56:59], v[52:55], v[172:175], v[56:59]
	v_mfma_f32_16x16x32_bf16 v[28:31], v[40:43], v[190:193], v[28:31]
	v_mfma_f32_16x16x32_bf16 v[28:31], v[44:47], v[196:199], v[28:31]
	v_mfma_f32_16x16x32_bf16 v[24:27], v[48:51], v[190:193], v[24:27]
	v_mfma_f32_16x16x32_bf16 v[24:27], v[52:55], v[196:199], v[24:27]
	v_mfma_f32_16x16x32_bf16 v[12:15], v[40:43], v[200:203], v[12:15]
	v_mfma_f32_16x16x32_bf16 v[12:15], v[44:47], v[204:207], v[12:15]
	v_mfma_f32_16x16x32_bf16 v[8:11], v[48:51], v[200:203], v[8:11]
	v_mfma_f32_16x16x32_bf16 v[8:11], v[52:55], v[204:207], v[8:11]
	v_mfma_f32_16x16x32_bf16 v[36:39], v[64:67], v[156:159], v[36:39]
	v_mfma_f32_16x16x32_bf16 v[36:39], v[100:103], v[172:175], v[36:39]
	v_mfma_f32_16x16x32_bf16 v[32:35], v[120:123], v[156:159], v[32:35]
	v_mfma_f32_16x16x32_bf16 v[32:35], v[124:127], v[172:175], v[32:35]
	v_mfma_f32_16x16x32_bf16 v[20:23], v[64:67], v[190:193], v[20:23]
	v_mfma_f32_16x16x32_bf16 v[20:23], v[100:103], v[196:199], v[20:23]
	v_mfma_f32_16x16x32_bf16 v[16:19], v[120:123], v[190:193], v[16:19]
	v_mfma_f32_16x16x32_bf16 v[16:19], v[124:127], v[196:199], v[16:19]
	v_mfma_f32_16x16x32_bf16 v[4:7], v[64:67], v[200:203], v[4:7]
	v_mfma_f32_16x16x32_bf16 v[4:7], v[100:103], v[204:207], v[4:7]
	v_mfma_f32_16x16x32_bf16 v[0:3], v[120:123], v[200:203], v[0:3]
	v_mfma_f32_16x16x32_bf16 v[0:3], v[124:127], v[204:207], v[0:3]
	v_mfma_f32_16x16x32_bf16 v[40:43], v[64:67], v[140:143], v[72:75]
	v_mfma_f32_16x16x32_bf16 v[40:43], v[100:103], v[144:147], v[40:43]
	v_mfma_f32_16x16x32_bf16 v[44:47], v[120:123], v[140:143], v[68:71]
	v_mfma_f32_16x16x32_bf16 v[44:47], v[124:127], v[144:147], v[44:47]
	s_barrier
	s_add_i32 s67, 0, 0x18000
	s_add_i32 s87, 0, 0x1c000
	v_add_u32_e32 v68, s67, v194
	v_add_u32_e32 v72, s87, v194
	ds_read_b128 v[48:51], v68
	ds_read_b128 v[52:55], v68 offset:1024
	ds_read_b128 v[64:67], v68 offset:2048
	ds_read_b128 v[68:71], v68 offset:3072
	ds_read_b128 v[100:103], v72
	ds_read_b128 v[120:123], v72 offset:1024
	ds_read_b128 v[124:127], v72 offset:2048
	ds_read_b128 v[140:143], v72 offset:3072
	s_add_u32 s94, s94, 0x80000
	s_addc_u32 s95, s95, 0
	s_mov_b32 m0, s68
	v_lshl_add_u64 v[156:157], s[94:95], 0, v[176:177]
	ds_read_b128 v[72:75], v195 offset:32768
	ds_read_b128 v[144:147], v195 offset:33792
	ds_read_b128 v[172:175], v195 offset:34816
	ds_read_b128 v[190:193], v195 offset:35840
	ds_read_b128 v[196:199], v195 offset:36864
	ds_read_b128 v[200:203], v195 offset:37888
	ds_read_b128 v[204:207], v195 offset:38912
	ds_read_b128 v[208:211], v195 offset:39936
	global_load_lds_dwordx4 v[156:157], off
	v_lshl_add_u64 v[156:157], s[94:95], 0, v[180:181]
	s_mov_b32 m0, s69
	s_nop 0
	global_load_lds_dwordx4 v[156:157], off
	s_waitcnt vmcnt(8)
	s_waitcnt lgkmcnt(0)
	s_barrier
	s_waitcnt lgkmcnt(0)
	v_mfma_f32_16x16x32_bf16 v[156:159], v[48:51], v[72:75], v[168:171]
	v_mfma_f32_16x16x32_bf16 v[168:171], v[52:55], v[144:147], v[156:159]
	v_mfma_f32_16x16x32_bf16 v[156:159], v[64:67], v[72:75], v[164:167]
	v_mfma_f32_16x16x32_bf16 v[164:167], v[68:71], v[144:147], v[156:159]
	v_mfma_f32_16x16x32_bf16 v[152:155], v[48:51], v[172:175], v[152:155]
	v_mfma_f32_16x16x32_bf16 v[152:155], v[52:55], v[190:193], v[152:155]
	v_mfma_f32_16x16x32_bf16 v[148:151], v[64:67], v[172:175], v[148:151]
	v_mfma_f32_16x16x32_bf16 v[148:151], v[68:71], v[190:193], v[148:151]
	v_mfma_f32_16x16x32_bf16 v[116:119], v[48:51], v[196:199], v[116:119]
	v_mfma_f32_16x16x32_bf16 v[116:119], v[52:55], v[200:203], v[116:119]
	v_mfma_f32_16x16x32_bf16 v[112:115], v[64:67], v[196:199], v[112:115]
	v_mfma_f32_16x16x32_bf16 v[112:115], v[68:71], v[200:203], v[112:115]
	v_mfma_f32_16x16x32_bf16 v[96:99], v[48:51], v[204:207], v[96:99]
	v_mfma_f32_16x16x32_bf16 v[96:99], v[52:55], v[208:211], v[96:99]
	v_mfma_f32_16x16x32_bf16 v[92:95], v[64:67], v[204:207], v[92:95]
	v_mfma_f32_16x16x32_bf16 v[92:95], v[68:71], v[208:211], v[92:95]
	v_mfma_f32_16x16x32_bf16 v[156:159], v[100:103], v[72:75], v[160:163]
	v_mfma_f32_16x16x32_bf16 v[160:163], v[120:123], v[144:147], v[156:159]
	v_mfma_f32_16x16x32_bf16 v[72:75], v[124:127], v[72:75], v[136:139]
	v_mfma_f32_16x16x32_bf16 v[156:159], v[140:143], v[144:147], v[72:75]
	v_mfma_f32_16x16x32_bf16 v[72:75], v[100:103], v[172:175], v[132:135]
	v_mfma_f32_16x16x32_bf16 v[132:135], v[120:123], v[190:193], v[72:75]
	v_mfma_f32_16x16x32_bf16 v[72:75], v[124:127], v[172:175], v[128:131]
	v_mfma_f32_16x16x32_bf16 v[128:131], v[140:143], v[190:193], v[72:75]
	v_mfma_f32_16x16x32_bf16 v[72:75], v[100:103], v[196:199], v[108:111]
	v_mfma_f32_16x16x32_bf16 v[108:111], v[120:123], v[200:203], v[72:75]
	v_mfma_f32_16x16x32_bf16 v[72:75], v[124:127], v[196:199], v[104:107]
	v_mfma_f32_16x16x32_bf16 v[104:107], v[140:143], v[200:203], v[72:75]
	v_mfma_f32_16x16x32_bf16 v[72:75], v[100:103], v[204:207], v[88:91]
	v_mfma_f32_16x16x32_bf16 v[88:91], v[120:123], v[208:211], v[72:75]
	v_mfma_f32_16x16x32_bf16 v[72:75], v[124:127], v[204:207], v[84:87]
	v_mfma_f32_16x16x32_bf16 v[84:87], v[140:143], v[208:211], v[72:75]
	s_barrier
	s_add_i32 s67, s67, s56
	s_nop 3
	v_lshl_add_u64 v[72:73], v[212:213], 0, s[30:31]
	s_mov_b32 m0, s67
	ds_read_b128 v[136:139], v195 offset:49152
	ds_read_b128 v[144:147], v195 offset:50176
	ds_read_b128 v[172:175], v195 offset:51200
	ds_read_b128 v[190:193], v195 offset:52224
	ds_read_b128 v[196:199], v195 offset:53248
	ds_read_b128 v[200:203], v195 offset:54272
	ds_read_b128 v[204:207], v195 offset:55296
	ds_read_b128 v[208:211], v195 offset:56320
	global_load_lds_dwordx4 v[72:73], off
	s_add_i32 m0, s67, 0x2000
	s_add_u32 s92, s92, 0x80080
	v_lshl_add_u64 v[72:73], v[214:215], 0, s[30:31]
	s_addc_u32 s93, s93, 0
	s_add_i32 s67, s87, s56
	global_load_lds_dwordx4 v[72:73], off
	v_lshl_add_u64 v[72:73], s[92:93], 0, v[178:179]
	s_mov_b32 m0, s67
	s_nop 0
	global_load_lds_dwordx4 v[72:73], off
	v_lshl_add_u64 v[72:73], s[92:93], 0, v[182:183]
	s_add_i32 m0, s67, 0x2000
	s_nop 0
	global_load_lds_dwordx4 v[72:73], off
	v_lshl_add_u64 v[72:73], v[224:225], 0, s[30:31]
	s_mov_b32 m0, s2
	s_nop 0
	global_load_lds_dwordx4 v[72:73], off
	v_lshl_add_u64 v[72:73], v[226:227], 0, s[30:31]
	s_mov_b32 m0, s28
	s_nop 0
	global_load_lds_dwordx4 v[72:73], off
	s_waitcnt vmcnt(8)
	s_waitcnt lgkmcnt(0)
	s_barrier
	s_waitcnt lgkmcnt(0)
	v_mfma_f32_16x16x32_bf16 v[72:75], v[48:51], v[136:139], v[80:83]
	v_mfma_f32_16x16x32_bf16 v[80:83], v[52:55], v[144:147], v[72:75]
	v_mfma_f32_16x16x32_bf16 v[72:75], v[64:67], v[136:139], v[76:79]
	v_mfma_f32_16x16x32_bf16 v[76:79], v[68:71], v[144:147], v[72:75]
	v_mfma_f32_16x16x32_bf16 v[60:63], v[48:51], v[172:175], v[60:63]
	v_mfma_f32_16x16x32_bf16 v[60:63], v[52:55], v[190:193], v[60:63]
	v_mfma_f32_16x16x32_bf16 v[56:59], v[64:67], v[172:175], v[56:59]
	v_mfma_f32_16x16x32_bf16 v[56:59], v[68:71], v[190:193], v[56:59]
	v_mfma_f32_16x16x32_bf16 v[28:31], v[48:51], v[196:199], v[28:31]
	v_mfma_f32_16x16x32_bf16 v[28:31], v[52:55], v[200:203], v[28:31]
	v_mfma_f32_16x16x32_bf16 v[24:27], v[64:67], v[196:199], v[24:27]
	v_mfma_f32_16x16x32_bf16 v[24:27], v[68:71], v[200:203], v[24:27]
	v_mfma_f32_16x16x32_bf16 v[12:15], v[48:51], v[204:207], v[12:15]
	v_mfma_f32_16x16x32_bf16 v[12:15], v[52:55], v[208:211], v[12:15]
	v_mfma_f32_16x16x32_bf16 v[8:11], v[64:67], v[204:207], v[8:11]
	v_mfma_f32_16x16x32_bf16 v[8:11], v[68:71], v[208:211], v[8:11]
	v_mfma_f32_16x16x32_bf16 v[40:43], v[100:103], v[136:139], v[40:43]
	v_mfma_f32_16x16x32_bf16 v[72:75], v[120:123], v[144:147], v[40:43]
	v_mfma_f32_16x16x32_bf16 v[40:43], v[124:127], v[136:139], v[44:47]
	v_mfma_f32_16x16x32_bf16 v[68:71], v[140:143], v[144:147], v[40:43]
	v_mfma_f32_16x16x32_bf16 v[36:39], v[100:103], v[172:175], v[36:39]
	v_mfma_f32_16x16x32_bf16 v[36:39], v[120:123], v[190:193], v[36:39]
	v_mfma_f32_16x16x32_bf16 v[32:35], v[124:127], v[172:175], v[32:35]
	v_mfma_f32_16x16x32_bf16 v[32:35], v[140:143], v[190:193], v[32:35]
	v_mfma_f32_16x16x32_bf16 v[20:23], v[100:103], v[196:199], v[20:23]
	v_mfma_f32_16x16x32_bf16 v[20:23], v[120:123], v[200:203], v[20:23]
	v_mfma_f32_16x16x32_bf16 v[16:19], v[124:127], v[196:199], v[16:19]
	v_mfma_f32_16x16x32_bf16 v[16:19], v[140:143], v[200:203], v[16:19]
	v_mfma_f32_16x16x32_bf16 v[4:7], v[100:103], v[204:207], v[4:7]
	v_mfma_f32_16x16x32_bf16 v[4:7], v[120:123], v[208:211], v[4:7]
	v_mfma_f32_16x16x32_bf16 v[0:3], v[124:127], v[204:207], v[0:3]
	v_mfma_f32_16x16x32_bf16 v[0:3], v[140:143], v[208:211], v[0:3]
	s_barrier
	s_add_i32 s85, s85, 2
	s_add_u32 s10, s10, 0x100
	s_addc_u32 s11, s11, 0
	s_add_u32 s54, s54, 0x100
	s_addc_u32 s55, s55, 0
	s_cmp_gt_u32 s85, 29
	s_cbranch_scc0 .LBB0_639
	s_and_b64 vcc, exec, s[80:81]
	s_cbranch_vccz .LBB0_642
	s_barrier
